# gMLP next-group operand loads issued inside the LDS staging (on top of the P3 mid-tile DMA issue)
# speedup vs baseline: 1.0004x; 1.0004x over previous
; #define LAS __attribute__((address_space(3)))
; DI unsigned cvtpk(float lo, float hi) { f32x2_t v = {lo, hi}; bf16x2_t b = __builtin_convertvector(v, bf16x2_t); return __builtin_bit_cast(unsigned, b); }
; DI float bflo(unsigned w) { return __uint_as_float(w << 16); }
; DI float bfhi(unsigned w) { return __uint_as_float(w & 0xffff0000u); }
; DI void gmlp_unit(LAS char* lds, bf16_t* zU, const bf16_t* zV, const float* g_ln, const float* b_ln, const bf16_t* Wb, const float* b_sp, int R0, bool dummy = false) {
;     ...
;     GM_FETCH(0);
; #pragma unroll 1
;     for (int g = 0; g < 4; ++g) {
;         __syncthreads();
; #pragma unroll
;         for (int i = 0; i < 4; ++i) { const int s = lt + 32 * i;
;             *(LAS u32x4*)(Wl + s * WP + lc8 * 2) = pw[i];
;             const u32x4 w = pv[i]; float v[8] = {bflo(w.x), bfhi(w.x), bflo(w.y), bfhi(w.y), bflo(w.z), bfhi(w.z), bflo(w.w), bfhi(w.w)};
;             const float mu = St[2 * s], rsd = St[2 * s + 1];
; #pragma unroll
;             for (int e = 0; e < 8; ++e) v[e] = (v[e] - mu) * rsd * pg[e >> 2][e & 3] + pb[e >> 2][e & 3];
;             u32x4 o; o.x = cvtpk(v[0], v[1]); o.y = cvtpk(v[2], v[3]); o.z = cvtpk(v[4], v[5]); o.w = cvtpk(v[6], v[7]); *(LAS u32x4*)(Vn + s * VP + lc8 * 2) = o; }
;         __syncthreads();
;         if (g + 1 < 4) GM_FETCH(g + 1);
;         u32x2 uw[2][4]; float bs[2];
; #pragma unroll
;         for (int tb = 0; tb < 2; ++tb) { const int t = 32 * (2 * tp + tb) + r; bs[tb] = b_sp[g * 128 + t]; const bf16_t* up = zU + (size_t)(R0 + t) * 512 + g * 128 + 32 * cb + 4 * h;
; #pragma unroll
;             for (int k = 0; k < 4; ++k) uw[tb][k] = *(const u32x2*)(up + 8 * k); }
.LBB0_530:
	v_lshl_add_u64 v[218:219], s[86:87], 0, v[192:193]
	v_lshl_add_u64 v[2:3], v[184:185], 0, s[54:55]
	global_load_dwordx2 v[228:229], v[218:219], off offset:-32
	global_load_dwordx2 v[226:227], v[218:219], off offset:-16
	global_load_dwordx2 v[224:225], v[218:219], off
	global_load_dwordx2 v[222:223], v[218:219], off offset:16
	global_load_dword v220, v[2:3], off offset:-128
	global_load_dword v208, v[2:3], off
	v_lshl_add_u64 v[206:207], s[86:87], 0, v[196:197]
	global_load_dwordx2 v[216:217], v[206:207], off offset:-32
	global_load_dwordx2 v[214:215], v[206:207], off offset:-16
	global_load_dwordx2 v[212:213], v[206:207], off
	global_load_dwordx2 v[210:211], v[206:207], off offset:16
	s_add_i32 s6, 0, 0x12800
	s_waitcnt lgkmcnt(0)
	s_barrier
	ds_write_b128 v239, v[34:37]
	v_add_u32_e32 v1, s6, v234
	ds_read_b64 v[2:3], v1
	v_lshlrev_b32_e32 v4, 16, v38
	v_and_b32_e32 v5, 0xffff0000, v38
	v_lshlrev_b32_e32 v6, 16, v39
	v_and_b32_e32 v7, 0xffff0000, v39
	v_lshlrev_b32_e32 v8, 16, v40
	v_and_b32_e32 v9, 0xffff0000, v40
	v_lshlrev_b32_e32 v10, 16, v41
	v_and_b32_e32 v11, 0xffff0000, v41
	s_cmpk_eq_i32 s54, 0x600
	s_cbranch_scc1 .Lgm_f0
	v_lshl_add_u64 v[242:243], s[86:87], 0, v[194:195]
	global_load_dwordx4 v[34:37], v[242:243], off
	v_lshl_add_u64 v[242:243], s[86:87], 0, v[198:199]
	global_load_dwordx4 v[38:41], v[242:243], off
.Lgm_f0:
	s_waitcnt lgkmcnt(0)
	v_pk_add_f32 v[4:5], v[4:5], v[2:3] op_sel_hi:[1,0] neg_lo:[0,1] neg_hi:[0,1]
	v_pk_add_f32 v[6:7], v[6:7], v[2:3] op_sel_hi:[1,0] neg_lo:[0,1] neg_hi:[0,1]
	v_pk_add_f32 v[8:9], v[8:9], v[2:3] op_sel_hi:[1,0] neg_lo:[0,1] neg_hi:[0,1]
	v_pk_add_f32 v[10:11], v[10:11], v[2:3] op_sel_hi:[1,0] neg_lo:[0,1] neg_hi:[0,1]
	v_pk_mul_f32 v[4:5], v[2:3], v[4:5] op_sel:[1,0]
	v_pk_mul_f32 v[6:7], v[2:3], v[6:7] op_sel:[1,0]
	v_pk_mul_f32 v[8:9], v[2:3], v[8:9] op_sel:[1,0]
	v_pk_mul_f32 v[2:3], v[2:3], v[10:11] op_sel:[1,0]
	v_pk_fma_f32 v[4:5], v[70:71], v[4:5], v[78:79]
	v_pk_fma_f32 v[6:7], v[72:73], v[6:7], v[80:81]
	v_pk_fma_f32 v[8:9], v[66:67], v[8:9], v[74:75]
	v_pk_fma_f32 v[10:11], v[68:69], v[2:3], v[76:77]
	v_cvt_pk_bf16_f32 v2, v4, v5
	v_cvt_pk_bf16_f32 v3, v6, v7
	v_cvt_pk_bf16_f32 v4, v8, v9
	v_cvt_pk_bf16_f32 v5, v10, v11
	v_add_u32_e32 v1, v230, v235
	ds_write_b128 v1, v[2:5] offset:34816
	ds_write_b128 v239, v[42:45] offset:8704
	v_add_u32_e32 v2, s6, v236
	ds_read_b64 v[2:3], v2
	v_lshlrev_b32_e32 v4, 16, v46
	v_and_b32_e32 v5, 0xffff0000, v46
	v_lshlrev_b32_e32 v6, 16, v47
	v_and_b32_e32 v7, 0xffff0000, v47
	v_lshlrev_b32_e32 v8, 16, v48
	v_and_b32_e32 v9, 0xffff0000, v48
	v_lshlrev_b32_e32 v10, 16, v49
	v_and_b32_e32 v11, 0xffff0000, v49
	s_cmpk_eq_i32 s54, 0x600
	s_cbranch_scc1 .Lgm_f1
	v_lshl_add_u64 v[242:243], s[86:87], 0, v[190:191]
	global_load_dwordx4 v[42:45], v[242:243], off
	v_lshl_add_u64 v[242:243], s[86:87], 0, v[200:201]
	global_load_dwordx4 v[46:49], v[242:243], off
; #define LAS __attribute__((address_space(3)))
; DI unsigned cvtpk(float lo, float hi) { f32x2_t v = {lo, hi}; bf16x2_t b = __builtin_convertvector(v, bf16x2_t); return __builtin_bit_cast(unsigned, b); }
; DI float bflo(unsigned w) { return __uint_as_float(w << 16); }
; DI float bfhi(unsigned w) { return __uint_as_float(w & 0xffff0000u); }
; DI void gmlp_unit(LAS char* lds, bf16_t* zU, const bf16_t* zV, const float* g_ln, const float* b_ln, const bf16_t* Wb, const float* b_sp, int R0, bool dummy = false) {
;     ...
;     GM_FETCH(0);
; #pragma unroll 1
;     for (int g = 0; g < 4; ++g) {
;         __syncthreads();
; #pragma unroll
;         for (int i = 0; i < 4; ++i) { const int s = lt + 32 * i;
;             *(LAS u32x4*)(Wl + s * WP + lc8 * 2) = pw[i];
;             const u32x4 w = pv[i]; float v[8] = {bflo(w.x), bfhi(w.x), bflo(w.y), bfhi(w.y), bflo(w.z), bfhi(w.z), bflo(w.w), bfhi(w.w)};
;             const float mu = St[2 * s], rsd = St[2 * s + 1];
; #pragma unroll
;             for (int e = 0; e < 8; ++e) v[e] = (v[e] - mu) * rsd * pg[e >> 2][e & 3] + pb[e >> 2][e & 3];
;             u32x4 o; o.x = cvtpk(v[0], v[1]); o.y = cvtpk(v[2], v[3]); o.z = cvtpk(v[4], v[5]); o.w = cvtpk(v[6], v[7]); *(LAS u32x4*)(Vn + s * VP + lc8 * 2) = o; }
;         __syncthreads();
;         if (g + 1 < 4) GM_FETCH(g + 1);
.Lgm_f1:
	s_waitcnt lgkmcnt(0)
	v_pk_add_f32 v[4:5], v[4:5], v[2:3] op_sel_hi:[1,0] neg_lo:[0,1] neg_hi:[0,1]
	v_pk_add_f32 v[6:7], v[6:7], v[2:3] op_sel_hi:[1,0] neg_lo:[0,1] neg_hi:[0,1]
	v_pk_add_f32 v[8:9], v[8:9], v[2:3] op_sel_hi:[1,0] neg_lo:[0,1] neg_hi:[0,1]
	v_pk_add_f32 v[10:11], v[10:11], v[2:3] op_sel_hi:[1,0] neg_lo:[0,1] neg_hi:[0,1]
	v_pk_mul_f32 v[4:5], v[2:3], v[4:5] op_sel:[1,0]
	v_pk_mul_f32 v[6:7], v[2:3], v[6:7] op_sel:[1,0]
	v_pk_mul_f32 v[8:9], v[2:3], v[8:9] op_sel:[1,0]
	v_pk_mul_f32 v[2:3], v[2:3], v[10:11] op_sel:[1,0]
	v_pk_fma_f32 v[4:5], v[70:71], v[4:5], v[78:79]
	v_pk_fma_f32 v[6:7], v[72:73], v[6:7], v[80:81]
	v_pk_fma_f32 v[8:9], v[66:67], v[8:9], v[74:75]
	v_pk_fma_f32 v[10:11], v[68:69], v[2:3], v[76:77]
	v_cvt_pk_bf16_f32 v2, v4, v5
	v_cvt_pk_bf16_f32 v3, v6, v7
	v_cvt_pk_bf16_f32 v4, v8, v9
	v_cvt_pk_bf16_f32 v5, v10, v11
	ds_write_b128 v1, v[2:5] offset:45056
	ds_write_b128 v239, v[50:53] offset:17408
	v_add_u32_e32 v2, s6, v237
	ds_read_b64 v[2:3], v2
	v_lshlrev_b32_e32 v4, 16, v54
	v_and_b32_e32 v5, 0xffff0000, v54
	v_lshlrev_b32_e32 v6, 16, v55
	v_and_b32_e32 v7, 0xffff0000, v55
	v_lshlrev_b32_e32 v8, 16, v56
	v_and_b32_e32 v9, 0xffff0000, v56
	v_lshlrev_b32_e32 v10, 16, v57
	v_and_b32_e32 v11, 0xffff0000, v57
	s_cmpk_eq_i32 s54, 0x600
	s_cbranch_scc1 .Lgm_f2
	v_lshl_add_u64 v[242:243], s[86:87], 0, v[188:189]
	global_load_dwordx4 v[50:53], v[242:243], off
	v_lshl_add_u64 v[242:243], s[86:87], 0, v[202:203]
	global_load_dwordx4 v[54:57], v[242:243], off
.Lgm_f2:
	s_waitcnt lgkmcnt(0)
	v_pk_add_f32 v[4:5], v[4:5], v[2:3] op_sel_hi:[1,0] neg_lo:[0,1] neg_hi:[0,1]
	v_pk_add_f32 v[6:7], v[6:7], v[2:3] op_sel_hi:[1,0] neg_lo:[0,1] neg_hi:[0,1]
	v_pk_add_f32 v[8:9], v[8:9], v[2:3] op_sel_hi:[1,0] neg_lo:[0,1] neg_hi:[0,1]
	v_pk_add_f32 v[10:11], v[10:11], v[2:3] op_sel_hi:[1,0] neg_lo:[0,1] neg_hi:[0,1]
	v_pk_mul_f32 v[4:5], v[2:3], v[4:5] op_sel:[1,0]
	v_pk_mul_f32 v[6:7], v[2:3], v[6:7] op_sel:[1,0]
	v_pk_mul_f32 v[8:9], v[2:3], v[8:9] op_sel:[1,0]
	v_pk_mul_f32 v[2:3], v[2:3], v[10:11] op_sel:[1,0]
	v_pk_fma_f32 v[4:5], v[70:71], v[4:5], v[78:79]
	v_pk_fma_f32 v[6:7], v[72:73], v[6:7], v[80:81]
	v_pk_fma_f32 v[8:9], v[66:67], v[8:9], v[74:75]
	v_pk_fma_f32 v[10:11], v[68:69], v[2:3], v[76:77]
	v_cvt_pk_bf16_f32 v2, v4, v5
	v_cvt_pk_bf16_f32 v3, v6, v7
	v_cvt_pk_bf16_f32 v4, v8, v9
	v_cvt_pk_bf16_f32 v5, v10, v11
	ds_write_b128 v1, v[2:5] offset:55296
	ds_write_b128 v239, v[58:61] offset:26112
	v_add_u32_e32 v1, s6, v238
	ds_read_b64 v[2:3], v1
	v_lshlrev_b32_e32 v4, 16, v62
	v_and_b32_e32 v5, 0xffff0000, v62
	v_lshlrev_b32_e32 v6, 16, v63
	v_and_b32_e32 v7, 0xffff0000, v63
	v_lshlrev_b32_e32 v8, 16, v64
	v_and_b32_e32 v9, 0xffff0000, v64
	v_lshlrev_b32_e32 v10, 16, v65
	v_and_b32_e32 v11, 0xffff0000, v65
	s_cmpk_eq_i32 s54, 0x600
	s_cbranch_scc1 .Lgm_f3
	v_lshl_add_u64 v[242:243], s[86:87], 0, v[186:187]
	global_load_dwordx4 v[58:61], v[242:243], off
	v_lshl_add_u64 v[242:243], s[86:87], 0, v[204:205]
	global_load_dwordx4 v[62:65], v[242:243], off
.Lgm_f3:
	s_waitcnt lgkmcnt(0)
	v_pk_add_f32 v[4:5], v[4:5], v[2:3] op_sel_hi:[1,0] neg_lo:[0,1] neg_hi:[0,1]
	v_pk_add_f32 v[6:7], v[6:7], v[2:3] op_sel_hi:[1,0] neg_lo:[0,1] neg_hi:[0,1]
	v_pk_add_f32 v[8:9], v[8:9], v[2:3] op_sel_hi:[1,0] neg_lo:[0,1] neg_hi:[0,1]
	v_pk_add_f32 v[10:11], v[10:11], v[2:3] op_sel_hi:[1,0] neg_lo:[0,1] neg_hi:[0,1]
	v_pk_mul_f32 v[4:5], v[2:3], v[4:5] op_sel:[1,0]
	v_pk_mul_f32 v[6:7], v[2:3], v[6:7] op_sel:[1,0]
	v_pk_mul_f32 v[8:9], v[2:3], v[8:9] op_sel:[1,0]
	v_pk_mul_f32 v[2:3], v[2:3], v[10:11] op_sel:[1,0]
	v_pk_fma_f32 v[4:5], v[70:71], v[4:5], v[78:79]
	v_pk_fma_f32 v[6:7], v[72:73], v[6:7], v[80:81]
	v_pk_fma_f32 v[8:9], v[66:67], v[8:9], v[74:75]
	v_pk_fma_f32 v[10:11], v[68:69], v[2:3], v[76:77]
	v_cvt_pk_bf16_f32 v2, v4, v5
	v_cvt_pk_bf16_f32 v3, v6, v7
	v_cvt_pk_bf16_f32 v4, v8, v9
	v_cvt_pk_bf16_f32 v5, v10, v11
	s_cmpk_eq_i32 s54, 0x600
	ds_write_b128 v240, v[2:5] offset:55296
	s_waitcnt lgkmcnt(0)
	s_barrier
	s_cbranch_scc1 .LBB0_532
	v_lshl_add_u64 v[2:3], v[180:181], 0, s[54:55]
	global_load_dwordx4 v[66:69], v[2:3], off offset:528
	global_load_dwordx4 v[70:73], v[2:3], off offset:512
	v_lshl_add_u64 v[2:3], v[182:183], 0, s[54:55]
	global_load_dwordx4 v[74:77], v[2:3], off offset:528
	global_load_dwordx4 v[78:81], v[2:3], off offset:512
